# item-queue loop heads: redundant first workgroup barrier around the index broadcast removed
# baseline (speedup 1.0000x reference)
; #define LAS __attribute__((address_space(3)))
; __global__ void __launch_bounds__(512, 2) hybrid_fwd(Params p_unused) {
;     ...
;           for (;;) {
;               __syncthreads();
;               if (t0) *(LAS unsigned*)(lds + QWORD_OFF) = nxt_it;
;               __syncthreads();
;               const int it = (int)*(LAS unsigned*)(lds + QWORD_OFF);
;               if (it >= total) break;
;               if (t0) { const Params p = ldp(); nxt_it = atomicAdd((unsigned*)(p.ws + OFF_CTR) + l, 1u); }
.LBB0_667:
	s_waitcnt lgkmcnt(0)
	s_and_saveexec_b64 s[4:5], s[10:11]
	v_mov_b32_e32 v0, s76
	ds_write_b32 v0, v109
	s_or_b64 exec, exec, s[4:5]
	v_mov_b32_e32 v0, s76
	s_waitcnt lgkmcnt(0)
	s_barrier
	ds_read_b32 v0, v0
	s_waitcnt lgkmcnt(0)
	v_cmp_le_i32_e64 s[12:13], s0, v0
	v_readfirstlane_b32 s3, v0
	s_and_b64 vcc, exec, s[12:13]
	s_cbranch_vccnz .LBB0_666
	s_and_saveexec_b64 s[4:5], s[10:11]
	s_cbranch_execz .LBB0_673
	s_mov_b64 s[6:7], s[90:91]
	s_load_dwordx2 s[6:7], s[6:7], 0xa8
	s_waitcnt lgkmcnt(0)
	v_lshl_add_u64 v[2:3], v[130:131], 2, s[6:7]
	v_add_co_u32_e32 v2, vcc, 0xfab9000, v2
	s_nop 1
	v_addc_co_u32_e32 v3, vcc, 0, v3, vcc
	global_atomic_add v109, v[2:3], v230, off offset:2048 sc0
	s_or_b64 exec, exec, s[4:5]
	s_cmp_ge_i32 s3, s1
	s_mov_b64 s[4:5], -1
	s_cbranch_scc1 .LBB0_674

; #define LAS __attribute__((address_space(3)))
; __global__ void __launch_bounds__(512, 2) hybrid_fwd(Params p_unused) {
;     ...
;           for (;;) {
;               __syncthreads();
;               if (t0) *(LAS unsigned*)(lds + QWORD_OFF) = nxt_it;
;               __syncthreads();
;               const int it = (int)*(LAS unsigned*)(lds + QWORD_OFF);
;               if (it >= nit) break;
;               if (t0) { const Params p = ldp(); nxt_it = atomicAdd((unsigned*)(p.ws + OFF_CTR) + 2 + l, 1u); }
.LBB0_956:
	s_waitcnt lgkmcnt(0)
	s_and_saveexec_b64 s[4:5], s[10:11]
	v_mov_b32_e32 v0, s76
	ds_write_b32 v0, v80
	s_or_b64 exec, exec, s[4:5]
	v_mov_b32_e32 v0, s76
	s_waitcnt lgkmcnt(0)
	s_barrier
	ds_read_b32 v0, v0
	s_waitcnt lgkmcnt(0)
	v_cmp_le_i32_e64 s[12:13], s1, v0
	v_readfirstlane_b32 s3, v0
	s_and_b64 vcc, exec, s[12:13]
	s_cbranch_vccnz .LBB0_955
	s_and_saveexec_b64 s[4:5], s[10:11]
	s_cbranch_execz .LBB0_961
	s_mov_b64 s[6:7], s[90:91]
	s_load_dwordx2 s[6:7], s[6:7], 0xa8
	s_waitcnt lgkmcnt(0)
	v_lshl_add_u64 v[2:3], v[130:131], 2, s[6:7]
	v_add_co_u32_e32 v2, vcc, 0xfab9000, v2
	s_nop 1
	v_addc_co_u32_e32 v3, vcc, 0, v3, vcc
	global_atomic_add v80, v[2:3], v230, off offset:2056 sc0
